# hosted loads and stores issued behind the tile's first QK MFMA instead of at the tile head
# speedup vs baseline: 1.0080x; 1.0070x over previous
.LBB0_1451:
	s_add_i32 s34, s49, 0xfffe8000
	s_and_b32 s34, s34, 0x18000
	s_add_i32 s34, s34, 0
	v_add3_u32 v84, s34, v177, v176
	ds_read_b128 v[80:83], v84
	ds_read_b128 v[184:187], v84 offset:512
	v_add3_u32 v85, s34, v178, v176
	v_add3_u32 v84, s34, v179, v176
	v_add_u32_e32 v200, s34, v168
	v_add_u32_e32 v201, s34, v169
	s_and_b64 vcc, exec, s[26:27]
	s_waitcnt lgkmcnt(0)
	v_mfma_f32_32x32x16_bf16 v[96:111], v[80:83], v[112:115], v[0:15]
	s_cmp_eq_u32 s95, 0
	s_cbranch_scc1 .Lcjh_done_0
	s_cmp_eq_u32 s95, 1
	s_cbranch_scc0 .Lcjh_n1_0
	global_load_dwordx4 v[224:227], v222, s[100:101] nt
	v_add_u32_e32 v222, s94, v222
	global_load_dwordx4 v[228:231], v222, s[100:101] nt
	v_add_u32_e32 v222, s94, v222
	s_mov_b32 s90, 2
	s_add_i32 s95, s95, 1
	s_branch .Lcjh_done_0

.Lcjh_done_0:
	ds_read_b128 v[80:83], v85 offset:2048
	ds_read_b128 v[188:191], v85 offset:2560
	v_add3_u32 v85, s34, v180, v176
	s_mov_b64 s[34:35], -1
	ds_read_b128 v[192:195], v84 offset:4608
	s_waitcnt lgkmcnt(0)
	v_mfma_f32_32x32x16_bf16 v[96:111], v[80:83], v[116:119], v[96:111]
	ds_read_b128 v[80:83], v84 offset:4096
	s_waitcnt lgkmcnt(0)
	v_mfma_f32_32x32x16_bf16 v[96:111], v[80:83], v[120:123], v[96:111]
	ds_read_b128 v[80:83], v85 offset:6144
	ds_read_b128 v[196:199], v85 offset:6656
	s_waitcnt lgkmcnt(0)
	v_mfma_f32_32x32x16_bf16 v[96:111], v[80:83], v[124:127], v[96:111]
	v_mfma_f32_32x32x16_bf16 v[80:95], v[184:187], v[112:115], v[0:15]
	ds_read_b128 v[184:187], v200 offset:16384
	s_nop 9
	v_exp_f32_e32 v96, v96
	v_exp_f32_e32 v97, v97
	v_exp_f32_e32 v98, v98
	v_exp_f32_e32 v99, v99
	v_exp_f32_e32 v100, v100
	v_exp_f32_e32 v101, v101
	v_mfma_f32_32x32x16_bf16 v[80:95], v[188:191], v[116:119], v[80:95]
	v_exp_f32_e32 v102, v102
	v_exp_f32_e32 v103, v103
	v_cvt_pk_bf16_f32 v188, v96, v97
	v_cvt_pk_bf16_f32 v189, v98, v99
	v_cvt_pk_bf16_f32 v190, v100, v101
	v_cvt_pk_bf16_f32 v191, v102, v103
	v_exp_f32_e32 v104, v104
	v_mfma_f32_32x32x16_bf16 v[80:95], v[192:195], v[120:123], v[80:95]
	ds_read_b128 v[192:195], v200 offset:17408
	v_exp_f32_e32 v105, v105
	v_exp_f32_e32 v106, v106
	v_exp_f32_e32 v107, v107
	v_exp_f32_e32 v108, v108
	v_exp_f32_e32 v109, v109
	v_exp_f32_e32 v110, v110
	v_mfma_f32_32x32x16_bf16 v[80:95], v[196:199], v[124:127], v[80:95]
	v_exp_f32_e32 v111, v111
	s_waitcnt lgkmcnt(0)
	v_mfma_f32_32x32x16_bf16 v[64:79], v[184:187], v[188:191], v[64:79]
	ds_read_b128 v[184:187], v201 offset:16896
	ds_read_b128 v[196:199], v201 offset:17920
	s_nop 6
	v_exp_f32_e32 v80, v80
	v_exp_f32_e32 v81, v81
	v_exp_f32_e32 v82, v82
	v_exp_f32_e32 v83, v83
	v_exp_f32_e32 v84, v84
	v_exp_f32_e32 v85, v85
	s_waitcnt lgkmcnt(0)
	v_mfma_f32_32x32x16_bf16 v[48:63], v[184:187], v[188:191], v[48:63]
	ds_read_b128 v[184:187], v200 offset:20480
	v_exp_f32_e32 v86, v86
	v_exp_f32_e32 v87, v87
	v_exp_f32_e32 v88, v88
	v_exp_f32_e32 v89, v89
	v_exp_f32_e32 v90, v90
	v_exp_f32_e32 v91, v91
	v_mfma_f32_32x32x16_bf16 v[32:47], v[192:195], v[188:191], v[32:47]
	ds_read_b128 v[192:195], v200 offset:21504
	v_exp_f32_e32 v92, v92
	v_exp_f32_e32 v93, v93
	v_exp_f32_e32 v94, v94
	v_exp_f32_e32 v95, v95
	v_mfma_f32_32x32x16_bf16 v[16:31], v[196:199], v[188:191], v[16:31]
	v_cvt_pk_bf16_f32 v188, v104, v105
	v_cvt_pk_bf16_f32 v189, v106, v107
	v_cvt_pk_bf16_f32 v190, v108, v109
	v_cvt_pk_bf16_f32 v191, v110, v111
	s_waitcnt lgkmcnt(0)
	s_nop 0
	v_mfma_f32_32x32x16_bf16 v[64:79], v[184:187], v[188:191], v[64:79]
	ds_read_b128 v[184:187], v201 offset:20992
	ds_read_b128 v[196:199], v201 offset:22016
	s_waitcnt lgkmcnt(0)
	v_mfma_f32_32x32x16_bf16 v[48:63], v[184:187], v[188:191], v[48:63]
	ds_read_b128 v[184:187], v200 offset:24576
	v_mfma_f32_32x32x16_bf16 v[32:47], v[192:195], v[188:191], v[32:47]
	ds_read_b128 v[192:195], v200 offset:25600
	v_mfma_f32_32x32x16_bf16 v[16:31], v[196:199], v[188:191], v[16:31]
	v_cvt_pk_bf16_f32 v188, v80, v81
	v_cvt_pk_bf16_f32 v189, v82, v83
	v_cvt_pk_bf16_f32 v190, v84, v85
	v_cvt_pk_bf16_f32 v191, v86, v87
	s_waitcnt lgkmcnt(0)
	s_nop 0
	v_mfma_f32_32x32x16_bf16 v[64:79], v[184:187], v[188:191], v[64:79]
	ds_read_b128 v[184:187], v201 offset:25088
	ds_read_b128 v[196:199], v201 offset:26112
	s_waitcnt lgkmcnt(0)
	v_mfma_f32_32x32x16_bf16 v[48:63], v[184:187], v[188:191], v[48:63]
	ds_read_b128 v[184:187], v200 offset:28672
	v_mfma_f32_32x32x16_bf16 v[32:47], v[192:195], v[188:191], v[32:47]
	ds_read_b128 v[192:195], v200 offset:29696
	v_mfma_f32_32x32x16_bf16 v[16:31], v[196:199], v[188:191], v[16:31]
	v_cvt_pk_bf16_f32 v188, v88, v89
	v_cvt_pk_bf16_f32 v189, v90, v91
	v_cvt_pk_bf16_f32 v190, v92, v93
	v_cvt_pk_bf16_f32 v191, v94, v95
	s_waitcnt lgkmcnt(0)
	s_nop 0
	v_mfma_f32_32x32x16_bf16 v[64:79], v[184:187], v[188:191], v[64:79]
	ds_read_b128 v[184:187], v201 offset:29184
	ds_read_b128 v[196:199], v201 offset:30208
	s_waitcnt lgkmcnt(0)
	v_mfma_f32_32x32x16_bf16 v[48:63], v[184:187], v[188:191], v[48:63]
	v_mfma_f32_32x32x16_bf16 v[32:47], v[192:195], v[188:191], v[32:47]
	v_mfma_f32_32x32x16_bf16 v[16:31], v[196:199], v[188:191], v[16:31]
	s_cbranch_vccz .Lcj_cnt_0
	s_waitcnt vmcnt(0)
	s_branch .LBB0_1448

.LBB0_1459:
	s_add_i32 s18, s22, 0xfffe8000
	s_and_b32 s18, s18, 0x18000
	s_add_i32 s18, s18, 0
	v_add3_u32 v84, s18, v177, v176
	ds_read_b128 v[80:83], v84
	ds_read_b128 v[152:155], v84 offset:512
	v_add3_u32 v85, s18, v178, v176
	v_add3_u32 v84, s18, v179, v176
	v_add_u32_e32 v209, s18, v168
	v_add_u32_e32 v211, s18, v169
	s_and_b64 vcc, exec, s[16:17]
	s_waitcnt lgkmcnt(0)
	v_mfma_f32_32x32x16_bf16 v[96:111], v[80:83], v[112:115], v[0:15]
	s_cmp_eq_u32 s95, 0
	s_cbranch_scc1 .Lcjh_done_1
	s_cmp_eq_u32 s95, 1
	s_cbranch_scc0 .Lcjh_n1_1
	global_load_dwordx4 v[224:227], v222, s[100:101] nt
	v_add_u32_e32 v222, s94, v222
	global_load_dwordx4 v[228:231], v222, s[100:101] nt
	v_add_u32_e32 v222, s94, v222
	s_mov_b32 s90, 2
	s_add_i32 s95, s95, 1
	s_branch .Lcjh_done_1

.Lcjh_done_1:
	ds_read_b128 v[80:83], v85 offset:2048
	ds_read_b128 v[156:159], v85 offset:2560
	v_add3_u32 v85, s18, v180, v176
	s_mov_b64 s[18:19], -1
	ds_read_b128 v[160:163], v84 offset:4608
	s_waitcnt lgkmcnt(0)
	v_mfma_f32_32x32x16_bf16 v[96:111], v[80:83], v[116:119], v[96:111]
	ds_read_b128 v[80:83], v84 offset:4096
	s_waitcnt lgkmcnt(0)
	v_mfma_f32_32x32x16_bf16 v[96:111], v[80:83], v[120:123], v[96:111]
	ds_read_b128 v[80:83], v85 offset:6144
	ds_read_b128 v[218:221], v85 offset:6656
	s_waitcnt lgkmcnt(0)
	v_mfma_f32_32x32x16_bf16 v[96:111], v[80:83], v[124:127], v[96:111]
	v_mfma_f32_32x32x16_bf16 v[80:95], v[152:155], v[112:115], v[0:15]
	ds_read_b128 v[152:155], v209 offset:16384
	s_nop 9
	v_exp_f32_e32 v96, v96
	v_exp_f32_e32 v97, v97
	v_exp_f32_e32 v98, v98
	v_exp_f32_e32 v99, v99
	v_exp_f32_e32 v100, v100
	v_exp_f32_e32 v101, v101
	v_mfma_f32_32x32x16_bf16 v[80:95], v[156:159], v[116:119], v[80:95]
	v_exp_f32_e32 v102, v102
	v_exp_f32_e32 v103, v103
	v_cvt_pk_bf16_f32 v156, v96, v97
	v_cvt_pk_bf16_f32 v157, v98, v99
	v_cvt_pk_bf16_f32 v158, v100, v101
	v_cvt_pk_bf16_f32 v159, v102, v103
	v_exp_f32_e32 v104, v104
	v_mfma_f32_32x32x16_bf16 v[80:95], v[160:163], v[120:123], v[80:95]
	ds_read_b128 v[160:163], v209 offset:17408
	v_exp_f32_e32 v105, v105
	v_exp_f32_e32 v106, v106
	v_exp_f32_e32 v107, v107
	v_exp_f32_e32 v108, v108
	v_exp_f32_e32 v109, v109
	v_exp_f32_e32 v110, v110
	v_mfma_f32_32x32x16_bf16 v[80:95], v[218:221], v[124:127], v[80:95]
	v_exp_f32_e32 v111, v111
	s_waitcnt lgkmcnt(0)
	v_mfma_f32_32x32x16_bf16 v[64:79], v[152:155], v[156:159], v[64:79]
	ds_read_b128 v[152:155], v211 offset:16896
	ds_read_b128 v[218:221], v211 offset:17920
	s_nop 6
	v_exp_f32_e32 v80, v80
	v_exp_f32_e32 v81, v81
	v_exp_f32_e32 v82, v82
	v_exp_f32_e32 v83, v83
	v_exp_f32_e32 v84, v84
	v_exp_f32_e32 v85, v85
	s_waitcnt lgkmcnt(0)
	v_mfma_f32_32x32x16_bf16 v[48:63], v[152:155], v[156:159], v[48:63]
	ds_read_b128 v[152:155], v209 offset:20480
	v_exp_f32_e32 v86, v86
	v_exp_f32_e32 v87, v87
	v_exp_f32_e32 v88, v88
	v_exp_f32_e32 v89, v89
	v_exp_f32_e32 v90, v90
	v_exp_f32_e32 v91, v91
	v_mfma_f32_32x32x16_bf16 v[32:47], v[160:163], v[156:159], v[32:47]
	ds_read_b128 v[160:163], v209 offset:21504
	v_exp_f32_e32 v92, v92
	v_exp_f32_e32 v93, v93
	v_exp_f32_e32 v94, v94
	v_exp_f32_e32 v95, v95
	v_mfma_f32_32x32x16_bf16 v[16:31], v[218:221], v[156:159], v[16:31]
	v_cvt_pk_bf16_f32 v156, v104, v105
	v_cvt_pk_bf16_f32 v157, v106, v107
	v_cvt_pk_bf16_f32 v158, v108, v109
	v_cvt_pk_bf16_f32 v159, v110, v111
	s_waitcnt lgkmcnt(0)
	s_nop 0
	v_mfma_f32_32x32x16_bf16 v[64:79], v[152:155], v[156:159], v[64:79]
	ds_read_b128 v[152:155], v211 offset:20992
	ds_read_b128 v[218:221], v211 offset:22016
	s_waitcnt lgkmcnt(0)
	v_mfma_f32_32x32x16_bf16 v[48:63], v[152:155], v[156:159], v[48:63]
	ds_read_b128 v[152:155], v209 offset:24576
	v_mfma_f32_32x32x16_bf16 v[32:47], v[160:163], v[156:159], v[32:47]
	ds_read_b128 v[160:163], v209 offset:25600
	v_mfma_f32_32x32x16_bf16 v[16:31], v[218:221], v[156:159], v[16:31]
	v_cvt_pk_bf16_f32 v156, v80, v81
	v_cvt_pk_bf16_f32 v157, v82, v83
	v_cvt_pk_bf16_f32 v158, v84, v85
	v_cvt_pk_bf16_f32 v159, v86, v87
	s_waitcnt lgkmcnt(0)
	s_nop 0
	v_mfma_f32_32x32x16_bf16 v[64:79], v[152:155], v[156:159], v[64:79]
	ds_read_b128 v[152:155], v211 offset:25088
	ds_read_b128 v[218:221], v211 offset:26112
	s_waitcnt lgkmcnt(0)
	v_mfma_f32_32x32x16_bf16 v[48:63], v[152:155], v[156:159], v[48:63]
	ds_read_b128 v[152:155], v209 offset:28672
	v_mfma_f32_32x32x16_bf16 v[32:47], v[160:163], v[156:159], v[32:47]
	ds_read_b128 v[160:163], v209 offset:29696
	v_mfma_f32_32x32x16_bf16 v[16:31], v[218:221], v[156:159], v[16:31]
	v_cvt_pk_bf16_f32 v156, v88, v89
	v_cvt_pk_bf16_f32 v157, v90, v91
	v_cvt_pk_bf16_f32 v158, v92, v93
	v_cvt_pk_bf16_f32 v159, v94, v95
	s_waitcnt lgkmcnt(0)
	s_nop 0
	v_mfma_f32_32x32x16_bf16 v[64:79], v[152:155], v[156:159], v[64:79]
	ds_read_b128 v[152:155], v211 offset:29184
	ds_read_b128 v[218:221], v211 offset:30208
	s_waitcnt lgkmcnt(0)
	v_mfma_f32_32x32x16_bf16 v[48:63], v[152:155], v[156:159], v[48:63]
	v_mfma_f32_32x32x16_bf16 v[32:47], v[160:163], v[156:159], v[32:47]
	v_mfma_f32_32x32x16_bf16 v[16:31], v[218:221], v[156:159], v[16:31]
	s_cbranch_vccz .Lcj_cnt_1
	s_waitcnt vmcnt(0)
	s_branch .LBB0_1456
